# v4 plus: o-proj fused epilogue stores widened to 16 B per lane as well (all three bf16 fused epilogues)
# speedup vs baseline: 1.0180x; 1.0008x over previous
.LBB0_978:
	s_or_b64 exec, exec, s[0:1]
	s_waitcnt vmcnt(0) lgkmcnt(0)
	s_barrier
	v_mov_b32_e32 v18, 0
	s_waitcnt lgkmcnt(0)
	ds_read_b32 v19, v18 offset:10240
	v_lshl_add_u32 v18, v237, 2, 0
	ds_read_b32 v20, v18 offset:8192
	v_add_u32_e32 v146, s33, v237
	v_ashrrev_i32_e32 v147, 31, v146
	s_waitcnt lgkmcnt(1)
	v_or_b32_e32 v21, v19, v239
	v_lshlrev_b64 v[146:147], 11, v[146:147]
	s_waitcnt vmcnt(35)
	v_lshlrev_b32_e32 v148, 16, v226
	v_and_b32_e32 v149, 0xffff0000, v226
	v_lshlrev_b32_e32 v150, 16, v227
	v_and_b32_e32 v151, 0xffff0000, v227
	s_waitcnt lgkmcnt(0)
	v_pk_mul_f32 v[152:153], v[228:229], v[20:21] op_sel_hi:[1,0]
	v_pk_mul_f32 v[154:155], v[230:231], v[20:21] op_sel_hi:[1,0]
	s_waitcnt vmcnt(3)
	v_pk_fma_f32 v[150:151], v[16:17], v[152:153], v[150:151]
	v_pk_fma_f32 v[148:149], v[14:15], v[154:155], v[148:149]
	v_mov_b32_e32 v19, 0x7fc00000
	v_cmp_ne_u32_e32 vcc, 0, v21
	v_lshl_add_u64 v[146:147], s[12:13], 0, v[146:147]
	v_lshl_add_u64 v[146:147], v[162:163], 1, v[146:147]
	v_cndmask_b32_e32 v21, v150, v19, vcc
	v_cndmask_b32_e32 v150, v151, v19, vcc
	v_cndmask_b32_e32 v151, v148, v19, vcc
	v_cndmask_b32_e32 v152, v149, v19, vcc
	v_cvt_pk_bf16_f32 v148, v151, v152
	v_cvt_pk_bf16_f32 v149, v21, v150
	v_mbcnt_lo_u32_b32 v160, -1, 0
	v_mbcnt_hi_u32_b32 v160, -1, v160
	v_lshrrev_b32_e32 v160, 4, v160
	v_lshlrev_b32_e32 v160, 3, v160
	v_mov_b32_e32 v161, 0
	v_mov_b32_e32 v244, v148
	v_mov_b32_e32 v245, v149
	v_mul_f32_e32 v148, v152, v152
	v_mul_f32_e32 v149, v150, v150
	v_fmac_f32_e32 v148, v151, v151
	v_fmac_f32_e32 v149, v21, v21
	v_add_f32_e32 v21, v148, v149
	v_lshlrev_b32_e32 v148, 16, v224
	v_and_b32_e32 v149, 0xffff0000, v224
	v_pk_mul_f32 v[144:145], v[144:145], v[20:21] op_sel_hi:[1,0]
	v_lshlrev_b32_e32 v150, 16, v225
	v_and_b32_e32 v151, 0xffff0000, v225
	v_pk_mul_f32 v[142:143], v[142:143], v[20:21] op_sel_hi:[1,0]
	s_waitcnt vmcnt(3)
	v_pk_fma_f32 v[144:145], v[10:11], v[144:145], v[148:149]
	v_pk_fma_f32 v[142:143], v[12:13], v[142:143], v[150:151]
	v_cndmask_b32_e32 v145, v145, v19, vcc
	v_cndmask_b32_e32 v150, v142, v19, vcc
	v_cndmask_b32_e32 v143, v143, v19, vcc
	v_cndmask_b32_e32 v144, v144, v19, vcc
	v_cvt_pk_bf16_f32 v142, v144, v145
	v_mul_f32_e32 v145, v145, v145
	v_fmac_f32_e32 v145, v144, v144
	v_mul_f32_e32 v144, v143, v143
	v_fmac_f32_e32 v144, v150, v150
	v_add_f32_e32 v144, v145, v144
	v_add_f32_e32 v21, v21, v144
	v_lshlrev_b32_e32 v144, 16, v222
	v_and_b32_e32 v145, 0xffff0000, v222
	v_lshlrev_b32_e32 v148, 16, v223
	v_and_b32_e32 v149, 0xffff0000, v223
	v_pk_mul_f32 v[138:139], v[138:139], v[20:21] op_sel_hi:[1,0]
	v_pk_mul_f32 v[140:141], v[140:141], v[20:21] op_sel_hi:[1,0]
	s_waitcnt vmcnt(2)
	v_pk_fma_f32 v[138:139], v[8:9], v[138:139], v[148:149]
	v_pk_fma_f32 v[140:141], v[6:7], v[140:141], v[144:145]
	v_cndmask_b32_e32 v145, v139, v19, vcc
	v_cndmask_b32_e32 v149, v141, v19, vcc
	v_cndmask_b32_e32 v144, v138, v19, vcc
	v_cndmask_b32_e32 v148, v140, v19, vcc
	v_mul_f32_e32 v138, v149, v149
	v_mul_f32_e32 v139, v145, v145
	v_fmac_f32_e32 v138, v148, v148
	v_fmac_f32_e32 v139, v144, v144
	v_add_f32_e32 v138, v138, v139
	v_add_f32_e32 v151, v138, v21
	v_lshlrev_b32_e32 v138, 16, v220
	v_and_b32_e32 v139, 0xffff0000, v220
	v_lshlrev_b32_e32 v140, 16, v221
	v_and_b32_e32 v141, 0xffff0000, v221
	v_pk_mul_f32 v[134:135], v[134:135], v[20:21] op_sel_hi:[1,0]
	v_pk_mul_f32 v[20:21], v[136:137], v[20:21] op_sel_hi:[1,0]
	s_waitcnt vmcnt(1)
	v_pk_fma_f32 v[134:135], v[4:5], v[134:135], v[140:141]
	v_pk_fma_f32 v[20:21], v[2:3], v[20:21], v[138:139]
	v_cndmask_b32_e32 v137, v135, v19, vcc
	v_cndmask_b32_e32 v139, v21, v19, vcc
	v_cndmask_b32_e32 v136, v134, v19, vcc
	v_cndmask_b32_e32 v138, v20, v19, vcc
	v_mul_f32_e32 v20, v139, v139
	v_mul_f32_e32 v21, v137, v137
	v_fmac_f32_e32 v20, v138, v138
	v_fmac_f32_e32 v21, v136, v136
	v_add_f32_e32 v20, v20, v21
	v_add_f32_e32 v20, v20, v151
	ds_bpermute_b32 v21, v1, v20
	v_cvt_pk_bf16_f32 v143, v150, v143
	v_mov_b32_e32 v246, v142
	v_mov_b32_e32 v247, v143
	s_nop 1
	v_permlane32_swap_b32_e32 v244, v246
	v_permlane32_swap_b32_e32 v245, v247
	s_nop 0
	v_permlane16_swap_b32_e32 v244, v246
	v_permlane16_swap_b32_e32 v245, v247
	v_lshl_add_u64 v[240:241], v[146:147], 0, v[160:161]
	global_store_dwordx4 v[240:241], v[244:247], off
	v_cvt_pk_bf16_f32 v134, v148, v149
	v_cvt_pk_bf16_f32 v135, v144, v145
	s_waitcnt lgkmcnt(0)
	v_add_f32_e32 v20, v20, v21
	ds_bpermute_b32 v21, v233, v20
	v_mov_b32_e32 v156, v134
	v_mov_b32_e32 v157, v135
	v_cvt_pk_bf16_f32 v134, v138, v139
	v_cvt_pk_bf16_f32 v135, v136, v137
	v_mov_b32_e32 v158, v134
	v_mov_b32_e32 v159, v135
	s_nop 1
	v_permlane32_swap_b32_e32 v156, v158
	v_permlane32_swap_b32_e32 v157, v159
	s_nop 0
	v_permlane16_swap_b32_e32 v156, v158
	v_permlane16_swap_b32_e32 v157, v159
	v_lshl_add_u64 v[240:241], v[146:147], 0, v[160:161]
	global_store_dwordx4 v[240:241], v[156:159], off offset:256
	s_and_saveexec_b64 s[0:1], s[4:5]
	s_cbranch_execz .LBB0_980
	v_lshl_add_u32 v134, v237, 4, s34
	s_waitcnt lgkmcnt(0)
	v_add_f32_e32 v20, v20, v21
	ds_write_b32 v134, v20 offset:16384
.LBB0_980:
	s_or_b64 exec, exec, s[0:1]
	ds_read_b32 v134, v18 offset:8256
	v_or_b32_e32 v20, 16, v237
	v_add_u32_e32 v136, s33, v20
	v_ashrrev_i32_e32 v137, 31, v136
	v_lshlrev_b32_e32 v138, 16, v218
	v_and_b32_e32 v139, 0xffff0000, v218
	s_waitcnt lgkmcnt(0)
	v_pk_mul_f32 v[132:133], v[132:133], v[134:135] op_sel_hi:[1,0]
	v_lshlrev_b64 v[136:137], 11, v[136:137]
	v_lshlrev_b32_e32 v140, 16, v219
	v_and_b32_e32 v141, 0xffff0000, v219
	v_pk_mul_f32 v[130:131], v[130:131], v[134:135] op_sel_hi:[1,0]
	v_pk_fma_f32 v[132:133], v[14:15], v[132:133], v[138:139]
	v_pk_fma_f32 v[130:131], v[16:17], v[130:131], v[140:141]
	v_cndmask_b32_e32 v138, v132, v19, vcc
	v_cndmask_b32_e32 v139, v133, v19, vcc
	v_lshl_add_u64 v[132:133], s[12:13], 0, v[136:137]
	v_cndmask_b32_e32 v21, v130, v19, vcc
	v_cndmask_b32_e32 v135, v131, v19, vcc
	v_cvt_pk_bf16_f32 v130, v138, v139
	v_cvt_pk_bf16_f32 v131, v21, v135
	v_lshl_add_u64 v[132:133], v[162:163], 1, v[132:133]
	v_mov_b32_e32 v244, v130
	v_mov_b32_e32 v245, v131
	v_mul_f32_e32 v130, v139, v139
	v_mul_f32_e32 v131, v135, v135
	v_fmac_f32_e32 v130, v138, v138
	v_fmac_f32_e32 v131, v21, v21
	v_add_f32_e32 v21, v130, v131
	v_lshlrev_b32_e32 v130, 16, v216
	v_and_b32_e32 v131, 0xffff0000, v216
	v_pk_mul_f32 v[128:129], v[128:129], v[134:135] op_sel_hi:[1,0]
	v_lshlrev_b32_e32 v136, 16, v217
	v_and_b32_e32 v137, 0xffff0000, v217
	v_pk_mul_f32 v[126:127], v[126:127], v[134:135] op_sel_hi:[1,0]
	v_pk_fma_f32 v[128:129], v[10:11], v[128:129], v[130:131]
	v_pk_fma_f32 v[126:127], v[12:13], v[126:127], v[136:137]
	v_cndmask_b32_e32 v129, v129, v19, vcc
	v_cndmask_b32_e32 v135, v126, v19, vcc
	v_cndmask_b32_e32 v127, v127, v19, vcc
	v_cndmask_b32_e32 v128, v128, v19, vcc
	v_cvt_pk_bf16_f32 v126, v128, v129
	v_mul_f32_e32 v129, v129, v129
	v_fmac_f32_e32 v129, v128, v128
	v_mul_f32_e32 v128, v127, v127
	v_fmac_f32_e32 v128, v135, v135
	v_add_f32_e32 v128, v129, v128
	v_add_f32_e32 v21, v21, v128
	v_lshlrev_b32_e32 v128, 16, v214
	v_and_b32_e32 v129, 0xffff0000, v214
	v_lshlrev_b32_e32 v130, 16, v215
	v_and_b32_e32 v131, 0xffff0000, v215
	v_pk_mul_f32 v[122:123], v[122:123], v[134:135] op_sel_hi:[1,0]
	v_pk_mul_f32 v[124:125], v[124:125], v[134:135] op_sel_hi:[1,0]
	v_pk_fma_f32 v[122:123], v[8:9], v[122:123], v[130:131]
	v_pk_fma_f32 v[124:125], v[6:7], v[124:125], v[128:129]
	v_cndmask_b32_e32 v129, v123, v19, vcc
	v_cndmask_b32_e32 v131, v125, v19, vcc
	v_cndmask_b32_e32 v128, v122, v19, vcc
	v_cndmask_b32_e32 v130, v124, v19, vcc
	v_mul_f32_e32 v122, v131, v131
	v_mul_f32_e32 v123, v129, v129
	v_fmac_f32_e32 v122, v130, v130
	v_fmac_f32_e32 v123, v128, v128
	v_add_f32_e32 v122, v122, v123
	v_add_f32_e32 v21, v122, v21
	v_lshlrev_b32_e32 v122, 16, v212
	v_and_b32_e32 v123, 0xffff0000, v212
	v_lshlrev_b32_e32 v124, 16, v213
	v_and_b32_e32 v125, 0xffff0000, v213
	v_pk_mul_f32 v[118:119], v[118:119], v[134:135] op_sel_hi:[1,0]
	v_pk_mul_f32 v[120:121], v[120:121], v[134:135] op_sel_hi:[1,0]
	v_pk_fma_f32 v[118:119], v[4:5], v[118:119], v[124:125]
	v_pk_fma_f32 v[120:121], v[2:3], v[120:121], v[122:123]
	v_cndmask_b32_e32 v123, v119, v19, vcc
	v_cndmask_b32_e32 v121, v121, v19, vcc
	v_cndmask_b32_e32 v122, v118, v19, vcc
	v_cndmask_b32_e32 v120, v120, v19, vcc
	v_mul_f32_e32 v19, v121, v121
	v_mul_f32_e32 v118, v123, v123
	v_fmac_f32_e32 v19, v120, v120
	v_fmac_f32_e32 v118, v122, v122
	v_add_f32_e32 v19, v19, v118
	v_add_f32_e32 v19, v19, v21
	ds_bpermute_b32 v21, v1, v19
	v_cvt_pk_bf16_f32 v127, v135, v127
	v_mov_b32_e32 v246, v126
	v_mov_b32_e32 v247, v127
	s_nop 1
	v_permlane32_swap_b32_e32 v244, v246
	v_permlane32_swap_b32_e32 v245, v247
	s_nop 0
	v_permlane16_swap_b32_e32 v244, v246
	v_permlane16_swap_b32_e32 v245, v247
	v_lshl_add_u64 v[240:241], v[132:133], 0, v[160:161]
	global_store_dwordx4 v[240:241], v[244:247], off
	v_cvt_pk_bf16_f32 v118, v130, v131
	v_cvt_pk_bf16_f32 v119, v128, v129
	s_waitcnt lgkmcnt(0)
	v_add_f32_e32 v19, v19, v21
	ds_bpermute_b32 v21, v233, v19
	v_mov_b32_e32 v156, v118
	v_mov_b32_e32 v157, v119
	v_cvt_pk_bf16_f32 v118, v120, v121
	v_cvt_pk_bf16_f32 v119, v122, v123
	v_mov_b32_e32 v158, v118
	v_mov_b32_e32 v159, v119
	s_nop 1
	v_permlane32_swap_b32_e32 v156, v158
	v_permlane32_swap_b32_e32 v157, v159
	s_nop 0
	v_permlane16_swap_b32_e32 v156, v158
	v_permlane16_swap_b32_e32 v157, v159
	v_lshl_add_u64 v[240:241], v[132:133], 0, v[160:161]
	global_store_dwordx4 v[240:241], v[156:159], off offset:256
	s_and_saveexec_b64 s[0:1], s[4:5]
	s_cbranch_execz .LBB0_982
	v_lshl_add_u32 v20, v20, 4, s34
	s_waitcnt lgkmcnt(0)
	v_add_f32_e32 v19, v19, v21
	ds_write_b32 v20, v19 offset:16384
.LBB0_982:
	s_or_b64 exec, exec, s[0:1]
	ds_read_b32 v118, v18 offset:8320
	v_or_b32_e32 v20, 32, v237
	v_add_u32_e32 v120, s33, v20
	v_ashrrev_i32_e32 v121, 31, v120
	v_lshlrev_b32_e32 v122, 16, v210
	v_and_b32_e32 v123, 0xffff0000, v210
	s_waitcnt lgkmcnt(0)
	v_pk_mul_f32 v[116:117], v[116:117], v[118:119] op_sel_hi:[1,0]
	v_lshlrev_b64 v[120:121], 11, v[120:121]
	v_lshlrev_b32_e32 v124, 16, v211
	v_and_b32_e32 v125, 0xffff0000, v211
	v_pk_mul_f32 v[114:115], v[114:115], v[118:119] op_sel_hi:[1,0]
	v_pk_fma_f32 v[116:117], v[14:15], v[116:117], v[122:123]
	v_mov_b32_e32 v19, 0x7fc00000
	v_pk_fma_f32 v[114:115], v[16:17], v[114:115], v[124:125]
	v_cndmask_b32_e32 v122, v116, v19, vcc
	v_cndmask_b32_e32 v123, v117, v19, vcc
	v_lshl_add_u64 v[116:117], s[12:13], 0, v[120:121]
	v_cndmask_b32_e32 v21, v114, v19, vcc
	v_cndmask_b32_e32 v119, v115, v19, vcc
	v_cvt_pk_bf16_f32 v114, v122, v123
	v_cvt_pk_bf16_f32 v115, v21, v119
	v_lshl_add_u64 v[116:117], v[162:163], 1, v[116:117]
	v_mov_b32_e32 v244, v114
	v_mov_b32_e32 v245, v115
	v_mul_f32_e32 v114, v123, v123
	v_mul_f32_e32 v115, v119, v119
	v_fmac_f32_e32 v114, v122, v122
	v_fmac_f32_e32 v115, v21, v21
	v_add_f32_e32 v21, v114, v115
	v_lshlrev_b32_e32 v114, 16, v208
	v_and_b32_e32 v115, 0xffff0000, v208
	v_pk_mul_f32 v[112:113], v[112:113], v[118:119] op_sel_hi:[1,0]
	v_lshlrev_b32_e32 v120, 16, v209
	v_and_b32_e32 v121, 0xffff0000, v209
	v_pk_mul_f32 v[110:111], v[110:111], v[118:119] op_sel_hi:[1,0]
	v_pk_fma_f32 v[112:113], v[10:11], v[112:113], v[114:115]
	v_pk_fma_f32 v[110:111], v[12:13], v[110:111], v[120:121]
	v_cndmask_b32_e32 v113, v113, v19, vcc
	v_cndmask_b32_e32 v119, v110, v19, vcc
	v_cndmask_b32_e32 v111, v111, v19, vcc
	v_cndmask_b32_e32 v112, v112, v19, vcc
	v_cvt_pk_bf16_f32 v110, v112, v113
	v_mul_f32_e32 v113, v113, v113
	v_fmac_f32_e32 v113, v112, v112
	v_mul_f32_e32 v112, v111, v111
	v_fmac_f32_e32 v112, v119, v119
	v_add_f32_e32 v112, v113, v112
	v_add_f32_e32 v21, v21, v112
	v_lshlrev_b32_e32 v112, 16, v206
	v_and_b32_e32 v113, 0xffff0000, v206
	v_lshlrev_b32_e32 v114, 16, v207
	v_and_b32_e32 v115, 0xffff0000, v207
	v_pk_mul_f32 v[106:107], v[106:107], v[118:119] op_sel_hi:[1,0]
	v_pk_mul_f32 v[108:109], v[108:109], v[118:119] op_sel_hi:[1,0]
	v_pk_fma_f32 v[106:107], v[8:9], v[106:107], v[114:115]
	v_pk_fma_f32 v[108:109], v[6:7], v[108:109], v[112:113]
	v_cndmask_b32_e32 v113, v107, v19, vcc
	v_cndmask_b32_e32 v115, v109, v19, vcc
	v_cndmask_b32_e32 v112, v106, v19, vcc
	v_cndmask_b32_e32 v114, v108, v19, vcc
	v_mul_f32_e32 v106, v115, v115
	v_mul_f32_e32 v107, v113, v113
	v_fmac_f32_e32 v106, v114, v114
	v_fmac_f32_e32 v107, v112, v112
	v_add_f32_e32 v106, v106, v107
	v_add_f32_e32 v21, v106, v21
	v_lshlrev_b32_e32 v106, 16, v204
	v_and_b32_e32 v107, 0xffff0000, v204
	v_lshlrev_b32_e32 v108, 16, v205
	v_and_b32_e32 v109, 0xffff0000, v205
	v_pk_mul_f32 v[102:103], v[102:103], v[118:119] op_sel_hi:[1,0]
	v_pk_mul_f32 v[104:105], v[104:105], v[118:119] op_sel_hi:[1,0]
	v_pk_fma_f32 v[102:103], v[4:5], v[102:103], v[108:109]
	v_pk_fma_f32 v[104:105], v[2:3], v[104:105], v[106:107]
	v_cndmask_b32_e32 v103, v103, v19, vcc
	v_cndmask_b32_e32 v108, v105, v19, vcc
	v_cndmask_b32_e32 v106, v102, v19, vcc
	v_cndmask_b32_e32 v107, v104, v19, vcc
	v_mul_f32_e32 v102, v108, v108
	v_mul_f32_e32 v104, v103, v103
	v_fmac_f32_e32 v102, v107, v107
	v_fmac_f32_e32 v104, v106, v106
	v_add_f32_e32 v102, v102, v104
	v_add_f32_e32 v21, v102, v21
	ds_bpermute_b32 v102, v1, v21
	v_cvt_pk_bf16_f32 v111, v119, v111
	v_mov_b32_e32 v246, v110
	v_mov_b32_e32 v247, v111
	s_nop 1
	v_permlane32_swap_b32_e32 v244, v246
	v_permlane32_swap_b32_e32 v245, v247
	s_nop 0
	v_permlane16_swap_b32_e32 v244, v246
	v_permlane16_swap_b32_e32 v245, v247
	v_lshl_add_u64 v[240:241], v[116:117], 0, v[160:161]
	global_store_dwordx4 v[240:241], v[244:247], off
	v_cvt_pk_bf16_f32 v104, v114, v115
	v_cvt_pk_bf16_f32 v105, v112, v113
	s_waitcnt lgkmcnt(0)
	v_add_f32_e32 v21, v21, v102
	ds_bpermute_b32 v102, v233, v21
	v_mov_b32_e32 v156, v104
	v_mov_b32_e32 v157, v105
	v_cvt_pk_bf16_f32 v104, v107, v108
	v_cvt_pk_bf16_f32 v105, v106, v103
	v_mov_b32_e32 v158, v104
	v_mov_b32_e32 v159, v105
	s_nop 1
	v_permlane32_swap_b32_e32 v156, v158
	v_permlane32_swap_b32_e32 v157, v159
	s_nop 0
	v_permlane16_swap_b32_e32 v156, v158
	v_permlane16_swap_b32_e32 v157, v159
	v_lshl_add_u64 v[240:241], v[116:117], 0, v[160:161]
	global_store_dwordx4 v[240:241], v[156:159], off offset:256
	s_and_saveexec_b64 s[0:1], s[4:5]
	s_cbranch_execz .LBB0_984
	v_lshl_add_u32 v20, v20, 4, s34
	s_waitcnt lgkmcnt(0)
	v_add_f32_e32 v21, v21, v102
	ds_write_b32 v20, v21 offset:16384
.LBB0_984:
	s_or_b64 exec, exec, s[0:1]
	s_waitcnt lgkmcnt(0)
	ds_read_b32 v102, v18 offset:8384
	v_or_b32_e32 v20, 48, v237
	v_add_u32_e32 v104, s33, v20
	v_ashrrev_i32_e32 v105, 31, v104
	v_lshlrev_b32_e32 v106, 16, v202
	v_and_b32_e32 v107, 0xffff0000, v202
	s_waitcnt lgkmcnt(0)
	v_pk_mul_f32 v[100:101], v[100:101], v[102:103] op_sel_hi:[1,0]
	v_lshlrev_b64 v[104:105], 11, v[104:105]
	v_lshlrev_b32_e32 v108, 16, v203
	v_and_b32_e32 v109, 0xffff0000, v203
	v_pk_mul_f32 v[98:99], v[98:99], v[102:103] op_sel_hi:[1,0]
	v_pk_fma_f32 v[100:101], v[14:15], v[100:101], v[106:107]
	v_pk_fma_f32 v[98:99], v[16:17], v[98:99], v[108:109]
	v_cndmask_b32_e32 v106, v100, v19, vcc
	v_cndmask_b32_e32 v107, v101, v19, vcc
	v_lshl_add_u64 v[100:101], s[12:13], 0, v[104:105]
	v_cndmask_b32_e32 v21, v98, v19, vcc
	v_cndmask_b32_e32 v103, v99, v19, vcc
	v_cvt_pk_bf16_f32 v98, v106, v107
	v_cvt_pk_bf16_f32 v99, v21, v103
	v_lshl_add_u64 v[100:101], v[162:163], 1, v[100:101]
	v_mov_b32_e32 v244, v98
	v_mov_b32_e32 v245, v99
	v_mul_f32_e32 v98, v107, v107
	v_mul_f32_e32 v99, v103, v103
	v_fmac_f32_e32 v98, v106, v106
	v_fmac_f32_e32 v99, v21, v21
	v_add_f32_e32 v21, v98, v99
	v_lshlrev_b32_e32 v98, 16, v200
	v_and_b32_e32 v99, 0xffff0000, v200
	v_pk_mul_f32 v[96:97], v[96:97], v[102:103] op_sel_hi:[1,0]
	v_lshlrev_b32_e32 v104, 16, v201
	v_and_b32_e32 v105, 0xffff0000, v201
	v_pk_mul_f32 v[94:95], v[94:95], v[102:103] op_sel_hi:[1,0]
	v_pk_fma_f32 v[96:97], v[10:11], v[96:97], v[98:99]
	v_pk_fma_f32 v[94:95], v[12:13], v[94:95], v[104:105]
	v_cndmask_b32_e32 v97, v97, v19, vcc
	v_cndmask_b32_e32 v103, v94, v19, vcc
	v_cndmask_b32_e32 v95, v95, v19, vcc
	v_cndmask_b32_e32 v96, v96, v19, vcc
	v_cvt_pk_bf16_f32 v94, v96, v97
	v_mul_f32_e32 v97, v97, v97
	v_fmac_f32_e32 v97, v96, v96
	v_mul_f32_e32 v96, v95, v95
	v_fmac_f32_e32 v96, v103, v103
	v_add_f32_e32 v96, v97, v96
	v_add_f32_e32 v21, v21, v96
	v_lshlrev_b32_e32 v96, 16, v198
	v_and_b32_e32 v97, 0xffff0000, v198
	v_lshlrev_b32_e32 v98, 16, v199
	v_and_b32_e32 v99, 0xffff0000, v199
	v_pk_mul_f32 v[90:91], v[90:91], v[102:103] op_sel_hi:[1,0]
	v_pk_mul_f32 v[92:93], v[92:93], v[102:103] op_sel_hi:[1,0]
	v_pk_fma_f32 v[90:91], v[8:9], v[90:91], v[98:99]
	v_pk_fma_f32 v[92:93], v[6:7], v[92:93], v[96:97]
	v_cndmask_b32_e32 v97, v91, v19, vcc
	v_cndmask_b32_e32 v99, v93, v19, vcc
	v_cndmask_b32_e32 v96, v90, v19, vcc
	v_cndmask_b32_e32 v98, v92, v19, vcc
	v_mul_f32_e32 v90, v99, v99
	v_mul_f32_e32 v91, v97, v97
	v_fmac_f32_e32 v90, v98, v98
	v_fmac_f32_e32 v91, v96, v96
	v_add_f32_e32 v90, v90, v91
	v_add_f32_e32 v21, v90, v21
	v_lshlrev_b32_e32 v90, 16, v196
	v_and_b32_e32 v91, 0xffff0000, v196
	v_lshlrev_b32_e32 v92, 16, v197
	v_and_b32_e32 v93, 0xffff0000, v197
	v_pk_mul_f32 v[86:87], v[86:87], v[102:103] op_sel_hi:[1,0]
	v_pk_mul_f32 v[88:89], v[88:89], v[102:103] op_sel_hi:[1,0]
	v_pk_fma_f32 v[86:87], v[4:5], v[86:87], v[92:93]
	v_pk_fma_f32 v[88:89], v[2:3], v[88:89], v[90:91]
	v_cndmask_b32_e32 v91, v87, v19, vcc
	v_cndmask_b32_e32 v89, v89, v19, vcc
	v_cndmask_b32_e32 v90, v86, v19, vcc
	v_cndmask_b32_e32 v88, v88, v19, vcc
	v_mul_f32_e32 v19, v89, v89
	v_mul_f32_e32 v86, v91, v91
	v_fmac_f32_e32 v19, v88, v88
	v_fmac_f32_e32 v86, v90, v90
	v_add_f32_e32 v19, v19, v86
	v_add_f32_e32 v19, v19, v21
	ds_bpermute_b32 v21, v1, v19
	v_cvt_pk_bf16_f32 v95, v103, v95
	v_mov_b32_e32 v246, v94
	v_mov_b32_e32 v247, v95
	s_nop 1
	v_permlane32_swap_b32_e32 v244, v246
	v_permlane32_swap_b32_e32 v245, v247
	s_nop 0
	v_permlane16_swap_b32_e32 v244, v246
	v_permlane16_swap_b32_e32 v245, v247
	v_lshl_add_u64 v[240:241], v[100:101], 0, v[160:161]
	global_store_dwordx4 v[240:241], v[244:247], off
	v_cvt_pk_bf16_f32 v86, v98, v99
	v_cvt_pk_bf16_f32 v87, v96, v97
	s_waitcnt lgkmcnt(0)
	v_add_f32_e32 v19, v19, v21
	ds_bpermute_b32 v21, v233, v19
	v_mov_b32_e32 v156, v86
	v_mov_b32_e32 v157, v87
	v_cvt_pk_bf16_f32 v86, v88, v89
	v_cvt_pk_bf16_f32 v87, v90, v91
	v_mov_b32_e32 v158, v86
	v_mov_b32_e32 v159, v87
	s_nop 1
	v_permlane32_swap_b32_e32 v156, v158
	v_permlane32_swap_b32_e32 v157, v159
	s_nop 0
	v_permlane16_swap_b32_e32 v156, v158
	v_permlane16_swap_b32_e32 v157, v159
	v_lshl_add_u64 v[240:241], v[100:101], 0, v[160:161]
	global_store_dwordx4 v[240:241], v[156:159], off offset:256
	s_and_saveexec_b64 s[0:1], s[4:5]
	s_cbranch_execz .LBB0_986
	v_lshl_add_u32 v20, v20, 4, s34
	s_waitcnt lgkmcnt(0)
	v_add_f32_e32 v19, v19, v21
	ds_write_b32 v20, v19 offset:16384
.LBB0_986:
	s_or_b64 exec, exec, s[0:1]
	v_add_u32_e32 v20, s30, v235
	v_lshl_add_u32 v20, v20, 2, 0
	ds_read_b32 v86, v20 offset:8704
	s_add_i32 s0, s30, 0x80
	v_or_b32_e32 v19, s0, v235
	v_add_u32_e32 v88, s33, v19
	v_ashrrev_i32_e32 v89, 31, v88
	v_lshlrev_b32_e32 v90, 16, v194
	v_and_b32_e32 v91, 0xffff0000, v194
	s_waitcnt lgkmcnt(0)
	v_pk_mul_f32 v[84:85], v[84:85], v[86:87] op_sel_hi:[1,0]
	v_lshlrev_b64 v[88:89], 11, v[88:89]
	v_lshlrev_b32_e32 v92, 16, v195
	v_and_b32_e32 v93, 0xffff0000, v195
	v_pk_mul_f32 v[82:83], v[82:83], v[86:87] op_sel_hi:[1,0]
	v_pk_fma_f32 v[84:85], v[14:15], v[84:85], v[90:91]
	v_mov_b32_e32 v21, 0x7fc00000
	v_pk_fma_f32 v[82:83], v[16:17], v[82:83], v[92:93]
	v_cndmask_b32_e32 v91, v84, v21, vcc
	v_cndmask_b32_e32 v92, v85, v21, vcc
	v_lshl_add_u64 v[84:85], s[12:13], 0, v[88:89]
	v_cndmask_b32_e32 v87, v82, v21, vcc
	v_cndmask_b32_e32 v90, v83, v21, vcc
	v_cvt_pk_bf16_f32 v82, v91, v92
	v_cvt_pk_bf16_f32 v83, v87, v90
	v_lshl_add_u64 v[84:85], v[162:163], 1, v[84:85]
	v_mov_b32_e32 v244, v82
	v_mov_b32_e32 v245, v83
	v_mul_f32_e32 v82, v92, v92
	v_mul_f32_e32 v83, v90, v90
	v_fmac_f32_e32 v82, v91, v91
	v_fmac_f32_e32 v83, v87, v87
	v_add_f32_e32 v87, v82, v83
	v_lshlrev_b32_e32 v82, 16, v192
	v_and_b32_e32 v83, 0xffff0000, v192
	v_pk_mul_f32 v[80:81], v[80:81], v[86:87] op_sel_hi:[1,0]
	v_lshlrev_b32_e32 v88, 16, v193
	v_and_b32_e32 v89, 0xffff0000, v193
	v_pk_mul_f32 v[78:79], v[78:79], v[86:87] op_sel_hi:[1,0]
	v_pk_fma_f32 v[80:81], v[10:11], v[80:81], v[82:83]
	v_pk_fma_f32 v[78:79], v[12:13], v[78:79], v[88:89]
	v_cndmask_b32_e32 v81, v81, v21, vcc
	v_cndmask_b32_e32 v88, v78, v21, vcc
	v_cndmask_b32_e32 v79, v79, v21, vcc
	v_cndmask_b32_e32 v80, v80, v21, vcc
	v_cvt_pk_bf16_f32 v78, v80, v81
	v_mul_f32_e32 v81, v81, v81
	v_fmac_f32_e32 v81, v80, v80
	v_mul_f32_e32 v80, v79, v79
	v_fmac_f32_e32 v80, v88, v88
	v_add_f32_e32 v80, v81, v80
	v_add_f32_e32 v87, v87, v80
	v_lshlrev_b32_e32 v80, 16, v190
	v_and_b32_e32 v81, 0xffff0000, v190
	v_lshlrev_b32_e32 v82, 16, v191
	v_and_b32_e32 v83, 0xffff0000, v191
	v_pk_mul_f32 v[74:75], v[74:75], v[86:87] op_sel_hi:[1,0]
	v_pk_mul_f32 v[76:77], v[76:77], v[86:87] op_sel_hi:[1,0]
	v_pk_fma_f32 v[74:75], v[8:9], v[74:75], v[82:83]
	v_pk_fma_f32 v[76:77], v[6:7], v[76:77], v[80:81]
	v_cndmask_b32_e32 v81, v75, v21, vcc
	v_cndmask_b32_e32 v83, v77, v21, vcc
	v_cndmask_b32_e32 v80, v74, v21, vcc
	v_cndmask_b32_e32 v82, v76, v21, vcc
	v_mul_f32_e32 v74, v83, v83
	v_mul_f32_e32 v75, v81, v81
	v_fmac_f32_e32 v74, v82, v82
	v_fmac_f32_e32 v75, v80, v80
	v_add_f32_e32 v74, v74, v75
	v_add_f32_e32 v87, v74, v87
	v_lshlrev_b32_e32 v74, 16, v188
	v_and_b32_e32 v75, 0xffff0000, v188
	v_lshlrev_b32_e32 v76, 16, v189
	v_and_b32_e32 v77, 0xffff0000, v189
	v_pk_mul_f32 v[70:71], v[70:71], v[86:87] op_sel_hi:[1,0]
	v_pk_mul_f32 v[72:73], v[72:73], v[86:87] op_sel_hi:[1,0]
	v_pk_fma_f32 v[70:71], v[4:5], v[70:71], v[76:77]
	v_pk_fma_f32 v[72:73], v[2:3], v[72:73], v[74:75]
	v_cndmask_b32_e32 v75, v71, v21, vcc
	v_cndmask_b32_e32 v77, v73, v21, vcc
	v_cndmask_b32_e32 v74, v70, v21, vcc
	v_cndmask_b32_e32 v76, v72, v21, vcc
	v_mul_f32_e32 v70, v77, v77
	v_mul_f32_e32 v71, v75, v75
	v_fmac_f32_e32 v70, v76, v76
	v_fmac_f32_e32 v71, v74, v74
	v_add_f32_e32 v70, v70, v71
	v_add_f32_e32 v70, v70, v87
	ds_bpermute_b32 v71, v1, v70
	v_cvt_pk_bf16_f32 v79, v88, v79
	v_mov_b32_e32 v246, v78
	v_mov_b32_e32 v247, v79
	s_nop 1
	v_permlane32_swap_b32_e32 v244, v246
	v_permlane32_swap_b32_e32 v245, v247
	s_nop 0
	v_permlane16_swap_b32_e32 v244, v246
	v_permlane16_swap_b32_e32 v245, v247
	v_lshl_add_u64 v[240:241], v[84:85], 0, v[160:161]
	global_store_dwordx4 v[240:241], v[244:247], off
	v_cvt_pk_bf16_f32 v72, v82, v83
	v_cvt_pk_bf16_f32 v73, v80, v81
	s_waitcnt lgkmcnt(0)
	v_add_f32_e32 v70, v70, v71
	ds_bpermute_b32 v71, v233, v70
	v_mov_b32_e32 v156, v72
	v_mov_b32_e32 v157, v73
	v_cvt_pk_bf16_f32 v72, v76, v77
	v_cvt_pk_bf16_f32 v73, v74, v75
	v_mov_b32_e32 v158, v72
	v_mov_b32_e32 v159, v73
	s_nop 1
	v_permlane32_swap_b32_e32 v156, v158
	v_permlane32_swap_b32_e32 v157, v159
	s_nop 0
	v_permlane16_swap_b32_e32 v156, v158
	v_permlane16_swap_b32_e32 v157, v159
	v_lshl_add_u64 v[240:241], v[84:85], 0, v[160:161]
	global_store_dwordx4 v[240:241], v[156:159], off offset:256
	s_and_saveexec_b64 s[0:1], s[4:5]
	s_cbranch_execz .LBB0_988
	v_lshl_add_u32 v72, v19, 4, s34
	s_waitcnt lgkmcnt(0)
	v_add_f32_e32 v70, v70, v71
	ds_write_b32 v72, v70 offset:16384
.LBB0_988:
	s_or_b64 exec, exec, s[0:1]
	ds_read_b32 v72, v20 offset:8768
	v_or_b32_e32 v70, 16, v19
	v_add_u32_e32 v74, s33, v70
	v_ashrrev_i32_e32 v75, 31, v74
	v_lshlrev_b32_e32 v76, 16, v186
	v_and_b32_e32 v77, 0xffff0000, v186
	s_waitcnt lgkmcnt(0)
	v_pk_mul_f32 v[68:69], v[68:69], v[72:73] op_sel_hi:[1,0]
	v_lshlrev_b64 v[74:75], 11, v[74:75]
	v_lshlrev_b32_e32 v78, 16, v187
	v_and_b32_e32 v79, 0xffff0000, v187
	v_pk_mul_f32 v[66:67], v[66:67], v[72:73] op_sel_hi:[1,0]
	v_pk_fma_f32 v[68:69], v[14:15], v[68:69], v[76:77]
	v_pk_fma_f32 v[66:67], v[16:17], v[66:67], v[78:79]
	v_cndmask_b32_e32 v76, v68, v21, vcc
	v_cndmask_b32_e32 v77, v69, v21, vcc
	v_lshl_add_u64 v[68:69], s[12:13], 0, v[74:75]
	v_cndmask_b32_e32 v71, v66, v21, vcc
	v_cndmask_b32_e32 v73, v67, v21, vcc
	v_cvt_pk_bf16_f32 v66, v76, v77
	v_cvt_pk_bf16_f32 v67, v71, v73
	v_lshl_add_u64 v[68:69], v[162:163], 1, v[68:69]
	v_mov_b32_e32 v244, v66
	v_mov_b32_e32 v245, v67
	v_mul_f32_e32 v66, v77, v77
	v_mul_f32_e32 v67, v73, v73
	v_fmac_f32_e32 v66, v76, v76
	v_fmac_f32_e32 v67, v71, v71
	v_add_f32_e32 v71, v66, v67
	v_lshlrev_b32_e32 v66, 16, v184
	v_and_b32_e32 v67, 0xffff0000, v184
	v_pk_mul_f32 v[64:65], v[64:65], v[72:73] op_sel_hi:[1,0]
	v_lshlrev_b32_e32 v74, 16, v185
	v_and_b32_e32 v75, 0xffff0000, v185
	v_pk_mul_f32 v[62:63], v[62:63], v[72:73] op_sel_hi:[1,0]
	v_pk_fma_f32 v[64:65], v[10:11], v[64:65], v[66:67]
	v_pk_fma_f32 v[62:63], v[12:13], v[62:63], v[74:75]
	v_cndmask_b32_e32 v65, v65, v21, vcc
	v_cndmask_b32_e32 v73, v62, v21, vcc
	v_cndmask_b32_e32 v63, v63, v21, vcc
	v_cndmask_b32_e32 v64, v64, v21, vcc
	v_cvt_pk_bf16_f32 v62, v64, v65
	v_mul_f32_e32 v65, v65, v65
	v_fmac_f32_e32 v65, v64, v64
	v_mul_f32_e32 v64, v63, v63
	v_fmac_f32_e32 v64, v73, v73
	v_add_f32_e32 v64, v65, v64
	v_add_f32_e32 v71, v71, v64
	v_lshlrev_b32_e32 v64, 16, v182
	v_and_b32_e32 v65, 0xffff0000, v182
	v_lshlrev_b32_e32 v66, 16, v183
	v_and_b32_e32 v67, 0xffff0000, v183
	v_pk_mul_f32 v[58:59], v[58:59], v[72:73] op_sel_hi:[1,0]
	v_pk_mul_f32 v[60:61], v[60:61], v[72:73] op_sel_hi:[1,0]
	v_pk_fma_f32 v[58:59], v[8:9], v[58:59], v[66:67]
	v_pk_fma_f32 v[60:61], v[6:7], v[60:61], v[64:65]
	v_cndmask_b32_e32 v65, v59, v21, vcc
	v_cndmask_b32_e32 v67, v61, v21, vcc
	v_cndmask_b32_e32 v64, v58, v21, vcc
	v_cndmask_b32_e32 v66, v60, v21, vcc
	v_mul_f32_e32 v58, v67, v67
	v_mul_f32_e32 v59, v65, v65
	v_fmac_f32_e32 v58, v66, v66
	v_fmac_f32_e32 v59, v64, v64
	v_add_f32_e32 v58, v58, v59
	v_add_f32_e32 v71, v58, v71
	v_lshlrev_b32_e32 v58, 16, v180
	v_and_b32_e32 v59, 0xffff0000, v180
	v_lshlrev_b32_e32 v60, 16, v181
	v_and_b32_e32 v61, 0xffff0000, v181
	v_pk_mul_f32 v[54:55], v[54:55], v[72:73] op_sel_hi:[1,0]
	v_pk_mul_f32 v[56:57], v[56:57], v[72:73] op_sel_hi:[1,0]
	v_pk_fma_f32 v[54:55], v[4:5], v[54:55], v[60:61]
	v_pk_fma_f32 v[56:57], v[2:3], v[56:57], v[58:59]
	v_cndmask_b32_e32 v55, v55, v21, vcc
	v_cndmask_b32_e32 v60, v57, v21, vcc
	v_cndmask_b32_e32 v58, v54, v21, vcc
	v_cndmask_b32_e32 v59, v56, v21, vcc
	v_mul_f32_e32 v21, v60, v60
	v_mul_f32_e32 v54, v55, v55
	v_fmac_f32_e32 v21, v59, v59
	v_fmac_f32_e32 v54, v58, v58
	v_add_f32_e32 v21, v21, v54
	v_add_f32_e32 v21, v21, v71
	ds_bpermute_b32 v54, v1, v21
	v_cvt_pk_bf16_f32 v63, v73, v63
	v_mov_b32_e32 v246, v62
	v_mov_b32_e32 v247, v63
	s_nop 1
	v_permlane32_swap_b32_e32 v244, v246
	v_permlane32_swap_b32_e32 v245, v247
	s_nop 0
	v_permlane16_swap_b32_e32 v244, v246
	v_permlane16_swap_b32_e32 v245, v247
	v_lshl_add_u64 v[240:241], v[68:69], 0, v[160:161]
	global_store_dwordx4 v[240:241], v[244:247], off
	v_cvt_pk_bf16_f32 v56, v66, v67
	v_cvt_pk_bf16_f32 v57, v64, v65
	s_waitcnt lgkmcnt(0)
	v_add_f32_e32 v21, v21, v54
	ds_bpermute_b32 v54, v233, v21
	v_mov_b32_e32 v156, v56
	v_mov_b32_e32 v157, v57
	v_cvt_pk_bf16_f32 v56, v59, v60
	v_cvt_pk_bf16_f32 v57, v58, v55
	v_mov_b32_e32 v158, v56
	v_mov_b32_e32 v159, v57
	s_nop 1
	v_permlane32_swap_b32_e32 v156, v158
	v_permlane32_swap_b32_e32 v157, v159
	s_nop 0
	v_permlane16_swap_b32_e32 v156, v158
	v_permlane16_swap_b32_e32 v157, v159
	v_lshl_add_u64 v[240:241], v[68:69], 0, v[160:161]
	global_store_dwordx4 v[240:241], v[156:159], off offset:256
	s_and_saveexec_b64 s[0:1], s[4:5]
	s_cbranch_execz .LBB0_990
	v_lshl_add_u32 v55, v70, 4, s34
	s_waitcnt lgkmcnt(0)
	v_add_f32_e32 v21, v21, v54
	ds_write_b32 v55, v21 offset:16384
.LBB0_990:
	s_or_b64 exec, exec, s[0:1]
	s_waitcnt lgkmcnt(0)
	ds_read_b32 v54, v18 offset:8832
	v_or_b32_e32 v21, 32, v19
	v_add_u32_e32 v56, s33, v21
	v_ashrrev_i32_e32 v57, 31, v56
	v_lshlrev_b32_e32 v58, 16, v178
	v_and_b32_e32 v59, 0xffff0000, v178
	s_waitcnt lgkmcnt(0)
	v_pk_mul_f32 v[52:53], v[52:53], v[54:55] op_sel_hi:[1,0]
	v_lshlrev_b64 v[56:57], 11, v[56:57]
	v_lshlrev_b32_e32 v60, 16, v179
	v_and_b32_e32 v61, 0xffff0000, v179
	v_pk_mul_f32 v[50:51], v[50:51], v[54:55] op_sel_hi:[1,0]
	v_pk_fma_f32 v[52:53], v[14:15], v[52:53], v[58:59]
	v_mov_b32_e32 v18, 0x7fc00000
	v_pk_fma_f32 v[50:51], v[16:17], v[50:51], v[60:61]
	v_cndmask_b32_e32 v59, v52, v18, vcc
	v_cndmask_b32_e32 v60, v53, v18, vcc
	v_lshl_add_u64 v[52:53], s[12:13], 0, v[56:57]
	v_cndmask_b32_e32 v55, v50, v18, vcc
	v_cndmask_b32_e32 v58, v51, v18, vcc
	v_cvt_pk_bf16_f32 v50, v59, v60
	v_cvt_pk_bf16_f32 v51, v55, v58
	v_lshl_add_u64 v[52:53], v[162:163], 1, v[52:53]
	v_mov_b32_e32 v244, v50
	v_mov_b32_e32 v245, v51
	v_mul_f32_e32 v50, v60, v60
	v_mul_f32_e32 v51, v58, v58
	v_fmac_f32_e32 v50, v59, v59
	v_fmac_f32_e32 v51, v55, v55
	v_add_f32_e32 v55, v50, v51
	v_lshlrev_b32_e32 v50, 16, v176
	v_and_b32_e32 v51, 0xffff0000, v176
	v_pk_mul_f32 v[48:49], v[48:49], v[54:55] op_sel_hi:[1,0]
	v_lshlrev_b32_e32 v56, 16, v177
	v_and_b32_e32 v57, 0xffff0000, v177
	v_pk_mul_f32 v[46:47], v[46:47], v[54:55] op_sel_hi:[1,0]
	v_pk_fma_f32 v[48:49], v[10:11], v[48:49], v[50:51]
	v_pk_fma_f32 v[46:47], v[12:13], v[46:47], v[56:57]
	v_cndmask_b32_e32 v49, v49, v18, vcc
	v_cndmask_b32_e32 v56, v46, v18, vcc
	v_cndmask_b32_e32 v47, v47, v18, vcc
	v_cndmask_b32_e32 v48, v48, v18, vcc
	v_cvt_pk_bf16_f32 v46, v48, v49
	v_mul_f32_e32 v49, v49, v49
	v_fmac_f32_e32 v49, v48, v48
	v_mul_f32_e32 v48, v47, v47
	v_fmac_f32_e32 v48, v56, v56
	v_add_f32_e32 v48, v49, v48
	v_add_f32_e32 v55, v55, v48
	v_lshlrev_b32_e32 v48, 16, v174
	v_and_b32_e32 v49, 0xffff0000, v174
	v_lshlrev_b32_e32 v50, 16, v175
	v_and_b32_e32 v51, 0xffff0000, v175
	v_pk_mul_f32 v[42:43], v[42:43], v[54:55] op_sel_hi:[1,0]
	v_pk_mul_f32 v[44:45], v[44:45], v[54:55] op_sel_hi:[1,0]
	v_pk_fma_f32 v[42:43], v[8:9], v[42:43], v[50:51]
	v_pk_fma_f32 v[44:45], v[6:7], v[44:45], v[48:49]
	v_cndmask_b32_e32 v49, v43, v18, vcc
	v_cndmask_b32_e32 v51, v45, v18, vcc
	v_cndmask_b32_e32 v48, v42, v18, vcc
	v_cndmask_b32_e32 v50, v44, v18, vcc
	v_mul_f32_e32 v42, v51, v51
	v_mul_f32_e32 v43, v49, v49
	v_fmac_f32_e32 v42, v50, v50
	v_fmac_f32_e32 v43, v48, v48
	v_add_f32_e32 v42, v42, v43
	v_add_f32_e32 v55, v42, v55
	v_lshlrev_b32_e32 v42, 16, v172
	v_and_b32_e32 v43, 0xffff0000, v172
	v_lshlrev_b32_e32 v44, 16, v173
	v_and_b32_e32 v45, 0xffff0000, v173
	v_pk_mul_f32 v[38:39], v[38:39], v[54:55] op_sel_hi:[1,0]
	v_pk_mul_f32 v[40:41], v[40:41], v[54:55] op_sel_hi:[1,0]
	v_pk_fma_f32 v[38:39], v[4:5], v[38:39], v[44:45]
	v_pk_fma_f32 v[40:41], v[2:3], v[40:41], v[42:43]
	v_cndmask_b32_e32 v43, v39, v18, vcc
	v_cndmask_b32_e32 v45, v41, v18, vcc
	v_cndmask_b32_e32 v42, v38, v18, vcc
	v_cndmask_b32_e32 v44, v40, v18, vcc
	v_mul_f32_e32 v38, v45, v45
	v_mul_f32_e32 v39, v43, v43
	v_fmac_f32_e32 v38, v44, v44
	v_fmac_f32_e32 v39, v42, v42
	v_add_f32_e32 v38, v38, v39
	v_add_f32_e32 v38, v38, v55
	ds_bpermute_b32 v39, v1, v38
	v_cvt_pk_bf16_f32 v47, v56, v47
	v_mov_b32_e32 v246, v46
	v_mov_b32_e32 v247, v47
	s_nop 1
	v_permlane32_swap_b32_e32 v244, v246
	v_permlane32_swap_b32_e32 v245, v247
	s_nop 0
	v_permlane16_swap_b32_e32 v244, v246
	v_permlane16_swap_b32_e32 v245, v247
	v_lshl_add_u64 v[240:241], v[52:53], 0, v[160:161]
	global_store_dwordx4 v[240:241], v[244:247], off
	v_cvt_pk_bf16_f32 v40, v50, v51
	v_cvt_pk_bf16_f32 v41, v48, v49
	s_waitcnt lgkmcnt(0)
	v_add_f32_e32 v38, v38, v39
	ds_bpermute_b32 v39, v233, v38
	v_mov_b32_e32 v156, v40
	v_mov_b32_e32 v157, v41
	v_cvt_pk_bf16_f32 v40, v44, v45
	v_cvt_pk_bf16_f32 v41, v42, v43
	v_mov_b32_e32 v158, v40
	v_mov_b32_e32 v159, v41
	s_nop 1
	v_permlane32_swap_b32_e32 v156, v158
	v_permlane32_swap_b32_e32 v157, v159
	s_nop 0
	v_permlane16_swap_b32_e32 v156, v158
	v_permlane16_swap_b32_e32 v157, v159
	v_lshl_add_u64 v[240:241], v[52:53], 0, v[160:161]
	global_store_dwordx4 v[240:241], v[156:159], off offset:256
	s_and_saveexec_b64 s[0:1], s[4:5]
	s_cbranch_execz .LBB0_992
	v_lshl_add_u32 v21, v21, 4, s34
	s_waitcnt lgkmcnt(0)
	v_add_f32_e32 v38, v38, v39
	ds_write_b32 v21, v38 offset:16384
.LBB0_992:
	s_or_b64 exec, exec, s[0:1]
	ds_read_b32 v20, v20 offset:8896
	v_or_b32_e32 v19, 48, v19
	v_add_u32_e32 v38, s33, v19
	s_waitcnt lgkmcnt(1)
	v_ashrrev_i32_e32 v39, 31, v38
	v_lshlrev_b32_e32 v42, 16, v171
	v_and_b32_e32 v43, 0xffff0000, v171
	s_waitcnt lgkmcnt(0)
	v_pk_mul_f32 v[34:35], v[34:35], v[20:21] op_sel_hi:[1,0]
	v_lshlrev_b64 v[38:39], 11, v[38:39]
	v_lshlrev_b32_e32 v40, 16, v170
	v_and_b32_e32 v41, 0xffff0000, v170
	v_pk_mul_f32 v[36:37], v[36:37], v[20:21] op_sel_hi:[1,0]
	v_pk_fma_f32 v[16:17], v[16:17], v[34:35], v[42:43]
	v_pk_fma_f32 v[14:15], v[14:15], v[36:37], v[40:41]
	v_cndmask_b32_e32 v21, v16, v18, vcc
	v_cndmask_b32_e32 v34, v17, v18, vcc
	v_lshl_add_u64 v[16:17], s[12:13], 0, v[38:39]
	v_cndmask_b32_e32 v35, v14, v18, vcc
	v_cndmask_b32_e32 v36, v15, v18, vcc
	v_cvt_pk_bf16_f32 v14, v35, v36
	v_cvt_pk_bf16_f32 v15, v21, v34
	v_lshl_add_u64 v[16:17], v[162:163], 1, v[16:17]
	v_mov_b32_e32 v244, v14
	v_mov_b32_e32 v245, v15
	v_mul_f32_e32 v14, v36, v36
	v_mul_f32_e32 v15, v34, v34
	v_fmac_f32_e32 v14, v35, v35
	v_fmac_f32_e32 v15, v21, v21
	v_add_f32_e32 v21, v14, v15
	v_lshlrev_b32_e32 v14, 16, v168
	v_and_b32_e32 v15, 0xffff0000, v168
	v_pk_mul_f32 v[32:33], v[32:33], v[20:21] op_sel_hi:[1,0]
	v_lshlrev_b32_e32 v34, 16, v169
	v_and_b32_e32 v35, 0xffff0000, v169
	v_pk_mul_f32 v[30:31], v[30:31], v[20:21] op_sel_hi:[1,0]
	v_pk_fma_f32 v[10:11], v[10:11], v[32:33], v[14:15]
	v_pk_fma_f32 v[12:13], v[12:13], v[30:31], v[34:35]
	v_cndmask_b32_e32 v11, v11, v18, vcc
	v_cndmask_b32_e32 v30, v12, v18, vcc
	v_cndmask_b32_e32 v31, v13, v18, vcc
	v_cndmask_b32_e32 v12, v10, v18, vcc
	v_cvt_pk_bf16_f32 v10, v12, v11
	v_mul_f32_e32 v11, v11, v11
	v_fmac_f32_e32 v11, v12, v12
	v_mul_f32_e32 v12, v31, v31
	v_fmac_f32_e32 v12, v30, v30
	v_add_f32_e32 v11, v11, v12
	v_lshlrev_b32_e32 v12, 16, v166
	v_and_b32_e32 v13, 0xffff0000, v166
	v_lshlrev_b32_e32 v14, 16, v167
	v_and_b32_e32 v15, 0xffff0000, v167
	v_pk_mul_f32 v[26:27], v[26:27], v[20:21] op_sel_hi:[1,0]
	v_pk_mul_f32 v[28:29], v[28:29], v[20:21] op_sel_hi:[1,0]
	v_pk_fma_f32 v[8:9], v[8:9], v[26:27], v[14:15]
	v_pk_fma_f32 v[6:7], v[6:7], v[28:29], v[12:13]
	v_cndmask_b32_e32 v26, v9, v18, vcc
	v_cndmask_b32_e32 v28, v7, v18, vcc
	v_add_f32_e32 v11, v21, v11
	v_cndmask_b32_e32 v21, v8, v18, vcc
	v_cndmask_b32_e32 v27, v6, v18, vcc
	v_mul_f32_e32 v6, v28, v28
	v_mul_f32_e32 v7, v26, v26
	v_fmac_f32_e32 v6, v27, v27
	v_fmac_f32_e32 v7, v21, v21
	v_add_f32_e32 v6, v6, v7
	v_add_f32_e32 v11, v6, v11
	v_lshlrev_b32_e32 v6, 16, v164
	v_and_b32_e32 v7, 0xffff0000, v164
	v_lshlrev_b32_e32 v8, 16, v165
	v_and_b32_e32 v9, 0xffff0000, v165
	v_pk_mul_f32 v[12:13], v[22:23], v[20:21] op_sel_hi:[1,0]
	v_pk_mul_f32 v[14:15], v[24:25], v[20:21] op_sel_hi:[1,0]
	v_pk_fma_f32 v[4:5], v[4:5], v[12:13], v[8:9]
	v_pk_fma_f32 v[2:3], v[2:3], v[14:15], v[6:7]
	v_cndmask_b32_e32 v7, v5, v18, vcc
	v_cndmask_b32_e32 v9, v3, v18, vcc
	v_cndmask_b32_e32 v6, v4, v18, vcc
	v_cndmask_b32_e32 v8, v2, v18, vcc
	v_mul_f32_e32 v2, v9, v9
	v_mul_f32_e32 v3, v7, v7
	v_fmac_f32_e32 v2, v8, v8
	v_fmac_f32_e32 v3, v6, v6
	v_add_f32_e32 v2, v2, v3
	v_add_f32_e32 v2, v2, v11
	ds_bpermute_b32 v3, v1, v2
	v_cvt_pk_bf16_f32 v11, v30, v31
	v_mov_b32_e32 v246, v10
	v_mov_b32_e32 v247, v11
	s_nop 1
	v_permlane32_swap_b32_e32 v244, v246
	v_permlane32_swap_b32_e32 v245, v247
	s_nop 0
	v_permlane16_swap_b32_e32 v244, v246
	v_permlane16_swap_b32_e32 v245, v247
	v_lshl_add_u64 v[240:241], v[16:17], 0, v[160:161]
	global_store_dwordx4 v[240:241], v[244:247], off
	v_cvt_pk_bf16_f32 v4, v27, v28
	v_cvt_pk_bf16_f32 v5, v21, v26
	s_waitcnt lgkmcnt(0)
	v_add_f32_e32 v2, v2, v3
	ds_bpermute_b32 v3, v233, v2
	v_mov_b32_e32 v156, v4
	v_mov_b32_e32 v157, v5
	v_cvt_pk_bf16_f32 v4, v8, v9
	v_cvt_pk_bf16_f32 v5, v6, v7
	v_mov_b32_e32 v158, v4
	v_mov_b32_e32 v159, v5
	s_nop 1
	v_permlane32_swap_b32_e32 v156, v158
	v_permlane32_swap_b32_e32 v157, v159
	s_nop 0
	v_permlane16_swap_b32_e32 v156, v158
	v_permlane16_swap_b32_e32 v157, v159
	v_lshl_add_u64 v[240:241], v[16:17], 0, v[160:161]
	global_store_dwordx4 v[240:241], v[156:159], off offset:256
	s_and_saveexec_b64 s[0:1], s[4:5]
	s_cbranch_execz .LBB0_994
	v_lshl_add_u32 v4, v19, 4, s34
	s_waitcnt lgkmcnt(0)
	v_add_f32_e32 v2, v2, v3
	ds_write_b32 v4, v2 offset:16384
